# seams: the CU's L1 invalidate issued by wave 1 at arrival (overlaps the arrival chain) instead of by thread 0 after the poll
# speedup vs baseline: 1.0133x; 1.0133x over previous
.LBB0_44:
	s_waitcnt vmcnt(0)
	s_barrier
	s_cmp_lg_u32 s54, 1
	s_cbranch_scc1 .Lb4_0
	s_mov_b64 s[98:99], exec
	s_mov_b64 exec, -1
	buffer_inv sc1
	s_waitcnt vmcnt(0)
	s_mov_b64 exec, s[98:99]
.Lb4_0:
	s_and_saveexec_b64 s[0:1], s[6:7]
	s_cbranch_execz .LBB0_107
	s_add_i32 s6, 0, 0x23fc0
	s_waitcnt vmcnt(3)
	v_mov_b32_e32 v2, s6
	s_waitcnt vmcnt(0) expcnt(0) lgkmcnt(0)
	ds_read_b32 v4, v2
	s_add_i32 s6, 0, 0x23fc4
	v_mov_b32_e32 v2, s6
	ds_read_b32 v2, v2
	s_waitcnt lgkmcnt(1)
	v_cmp_ne_u32_e32 vcc, 0, v4
	s_cbranch_vccnz .LBB0_71
	s_add_u32 s6, s40, 0x1e00200
	s_addc_u32 s7, s41, 0
	s_add_u32 s8, s40, 0x1e00400
	s_addc_u32 s9, s41, 0
	s_add_u32 s10, s40, 0x1e00500
	s_addc_u32 s11, s41, 0
	s_add_u32 s12, s40, 0x1e00600
	s_addc_u32 s13, s41, 0
	s_add_u32 s14, s40, 0x1e00700
	s_addc_u32 s15, s41, 0
	s_add_u32 s16, s40, 0x1e00800
	s_addc_u32 s17, s41, 0
	s_add_u32 s18, s40, 0x1e00900
	s_addc_u32 s19, s41, 0
	s_add_u32 s20, s40, 0x1e00a00
	s_addc_u32 s21, s41, 0
	s_add_u32 s22, s40, 0x1e00b00
	s_addc_u32 s23, s41, 0
	s_add_u32 s24, s40, 0x1e00c00
	s_addc_u32 s25, s41, 0
	s_add_u32 s26, s40, 0x1e00d00
	s_addc_u32 s27, s41, 0
	s_add_u32 s28, s40, 0x1e00e00
	s_addc_u32 s29, s41, 0
	s_add_u32 s30, s40, 0x1e00f00
	s_addc_u32 s31, s41, 0
	s_add_u32 s34, s40, 0x1e01000
	s_addc_u32 s35, s41, 0
	s_add_u32 s36, s40, 0x1e01100
	s_addc_u32 s37, s41, 0
	s_add_u32 s38, s40, 0x1e01200
	s_addc_u32 s39, s41, 0
	s_mul_i32 s59, s53, s56
	s_add_u32 s44, s40, 0x1e01300
	s_mul_i32 s59, s59, s52
	s_addc_u32 s45, s41, 0
	s_mov_b32 s60, 1
	v_mov_b32_e32 v18, 0
	s_branch .LBB0_48

.Lsm0_done:
	s_nop 0
	s_waitcnt vmcnt(0)

.LBB0_201:
	s_waitcnt vmcnt(0)
	s_waitcnt vmcnt(0)
	s_barrier
	s_cmp_lg_u32 s54, 1
	s_cbranch_scc1 .Lb4_1
	s_mov_b64 s[98:99], exec
	s_mov_b64 exec, -1
	buffer_inv sc1
	s_waitcnt vmcnt(0)
	s_mov_b64 exec, s[98:99]
.Lb4_1:
	s_and_saveexec_b64 s[0:1], s[6:7]
	s_cbranch_execz .LBB0_264
	s_add_i32 s6, 0, 0x23fc0
	v_mov_b32_e32 v2, s6
	s_waitcnt vmcnt(0) expcnt(0) lgkmcnt(0)
	ds_read_b32 v4, v2
	s_add_i32 s6, 0, 0x23fc4
	v_mov_b32_e32 v2, s6
	ds_read_b32 v2, v2
	s_waitcnt lgkmcnt(1)
	v_cmp_ne_u32_e32 vcc, 0, v4
	s_cbranch_vccnz .LBB0_228
	s_add_u32 s6, s40, 0x1e00200
	s_addc_u32 s7, s41, 0
	s_add_u32 s8, s40, 0x1e00400
	s_addc_u32 s9, s41, 0
	s_add_u32 s10, s40, 0x1e00500
	s_addc_u32 s11, s41, 0
	s_add_u32 s12, s40, 0x1e00600
	s_addc_u32 s13, s41, 0
	s_add_u32 s14, s40, 0x1e00700
	s_addc_u32 s15, s41, 0
	s_add_u32 s16, s40, 0x1e00800
	s_addc_u32 s17, s41, 0
	s_add_u32 s18, s40, 0x1e00900
	s_addc_u32 s19, s41, 0
	s_add_u32 s20, s40, 0x1e00a00
	s_addc_u32 s21, s41, 0
	s_add_u32 s22, s40, 0x1e00b00
	s_addc_u32 s23, s41, 0
	s_add_u32 s24, s40, 0x1e00c00
	s_addc_u32 s25, s41, 0
	s_add_u32 s26, s40, 0x1e00d00
	s_addc_u32 s27, s41, 0
	s_add_u32 s28, s40, 0x1e00e00
	s_addc_u32 s29, s41, 0
	s_add_u32 s30, s40, 0x1e00f00
	s_addc_u32 s31, s41, 0
	s_add_u32 s34, s40, 0x1e01000
	s_addc_u32 s35, s41, 0
	s_add_u32 s36, s40, 0x1e01100
	s_addc_u32 s37, s41, 0
	s_add_u32 s38, s40, 0x1e01200
	s_addc_u32 s39, s41, 0
	s_mul_i32 s59, s53, s56
	s_add_u32 s44, s40, 0x1e01300
	s_mul_i32 s59, s59, s52
	s_addc_u32 s45, s41, 0
	s_mov_b32 s60, 1
	v_mov_b32_e32 v18, 0
	s_branch .LBB0_205

.Lb4_2:
	s_and_saveexec_b64 s[4:5], s[6:7]
	s_cbranch_execz .LBB0_346
	s_add_i32 s6, 0, 0x23fc0
	v_mov_b32_e32 v2, s6
	s_waitcnt vmcnt(0) expcnt(0) lgkmcnt(0)
	ds_read_b32 v4, v2
	s_add_i32 s6, 0, 0x23fc4
	v_mov_b32_e32 v2, s6
	ds_read_b32 v2, v2
	s_waitcnt lgkmcnt(1)
	v_cmp_ne_u32_e32 vcc, 0, v4
	s_cbranch_vccnz .LBB0_310
	s_add_u32 s6, s40, 0x1e00200
	s_addc_u32 s7, s41, 0
	s_add_u32 s8, s40, 0x1e00400
	s_addc_u32 s9, s41, 0
	s_add_u32 s10, s40, 0x1e00500
	s_addc_u32 s11, s41, 0
	s_add_u32 s12, s40, 0x1e00600
	s_addc_u32 s13, s41, 0
	s_add_u32 s14, s40, 0x1e00700
	s_addc_u32 s15, s41, 0
	s_add_u32 s16, s40, 0x1e00800
	s_addc_u32 s17, s41, 0
	s_add_u32 s18, s40, 0x1e00900
	s_addc_u32 s19, s41, 0
	s_add_u32 s20, s40, 0x1e00a00
	s_addc_u32 s21, s41, 0
	s_add_u32 s22, s40, 0x1e00b00
	s_addc_u32 s23, s41, 0
	s_add_u32 s24, s40, 0x1e00c00
	s_addc_u32 s25, s41, 0
	s_add_u32 s26, s40, 0x1e00d00
	s_addc_u32 s27, s41, 0
	s_add_u32 s28, s40, 0x1e00e00
	s_addc_u32 s29, s41, 0
	s_add_u32 s30, s40, 0x1e00f00
	s_addc_u32 s31, s41, 0
	s_add_u32 s34, s40, 0x1e01000
	s_addc_u32 s35, s41, 0
	s_add_u32 s36, s40, 0x1e01100
	s_addc_u32 s37, s41, 0
	s_add_u32 s38, s40, 0x1e01200
	s_addc_u32 s39, s41, 0
	s_mul_i32 s59, s53, s56
	s_add_u32 s44, s40, 0x1e01300
	s_mul_i32 s59, s59, s52
	s_addc_u32 s45, s41, 0
	s_mov_b32 s60, 1
	v_mov_b32_e32 v18, 0
	s_branch .LBB0_287

.Lb4_4:
	s_and_saveexec_b64 s[0:1], s[6:7]
	s_cbranch_execz .LBB0_743
	s_add_i32 s6, 0, 0x23fc0
	v_mov_b32_e32 v2, s6
	s_waitcnt vmcnt(0) expcnt(0) lgkmcnt(0)
	ds_read_b32 v4, v2
	s_add_i32 s6, 0, 0x23fc4
	v_mov_b32_e32 v2, s6
	ds_read_b32 v2, v2
	s_waitcnt lgkmcnt(1)
	v_cmp_ne_u32_e32 vcc, 0, v4
	s_cbranch_vccnz .LBB0_707
	s_add_u32 s6, s40, 0x1e00200
	s_addc_u32 s7, s41, 0
	s_add_u32 s8, s40, 0x1e00400
	s_addc_u32 s9, s41, 0
	s_add_u32 s10, s40, 0x1e00500
	s_addc_u32 s11, s41, 0
	s_add_u32 s12, s40, 0x1e00600
	s_addc_u32 s13, s41, 0
	s_add_u32 s14, s40, 0x1e00700
	s_addc_u32 s15, s41, 0
	s_add_u32 s16, s40, 0x1e00800
	s_addc_u32 s17, s41, 0
	s_add_u32 s18, s40, 0x1e00900
	s_addc_u32 s19, s41, 0
	s_add_u32 s20, s40, 0x1e00a00
	s_addc_u32 s21, s41, 0
	s_add_u32 s22, s40, 0x1e00b00
	s_addc_u32 s23, s41, 0
	s_add_u32 s24, s40, 0x1e00c00
	s_addc_u32 s25, s41, 0
	s_add_u32 s26, s40, 0x1e00d00
	s_addc_u32 s27, s41, 0
	s_add_u32 s28, s40, 0x1e00e00
	s_addc_u32 s29, s41, 0
	s_add_u32 s30, s40, 0x1e00f00
	s_addc_u32 s31, s41, 0
	s_add_u32 s34, s40, 0x1e01000
	s_addc_u32 s35, s41, 0
	s_add_u32 s36, s40, 0x1e01100
	s_addc_u32 s37, s41, 0
	s_add_u32 s38, s40, 0x1e01200
	s_addc_u32 s39, s41, 0
	s_mul_i32 s33, s53, s56
	s_add_u32 s44, s40, 0x1e01300
	s_mul_i32 s33, s33, s52
	s_addc_u32 s45, s41, 0
	s_mov_b32 s57, 1
	v_mov_b32_e32 v18, 0
	s_branch .LBB0_684

.Lb4_5:
	s_and_saveexec_b64 s[0:1], s[4:5]
	s_cbranch_execz .LBB0_898
	s_add_i32 s4, 0, 0x23fc0
	v_mov_b32_e32 v2, s4
	s_waitcnt vmcnt(0) expcnt(0) lgkmcnt(0)
	ds_read_b32 v4, v2
	s_add_i32 s4, 0, 0x23fc4
	v_mov_b32_e32 v2, s4
	ds_read_b32 v2, v2
	s_waitcnt lgkmcnt(1)
	v_cmp_ne_u32_e32 vcc, 0, v4
	s_cbranch_vccnz .LBB0_862
	s_add_u32 s4, s40, 0x1e00200
	s_addc_u32 s5, s41, 0
	s_add_u32 s6, s40, 0x1e00400
	s_addc_u32 s7, s41, 0
	s_add_u32 s8, s40, 0x1e00500
	s_addc_u32 s9, s41, 0
	s_add_u32 s10, s40, 0x1e00600
	s_addc_u32 s11, s41, 0
	s_add_u32 s12, s40, 0x1e00700
	s_addc_u32 s13, s41, 0
	s_add_u32 s14, s40, 0x1e00800
	s_addc_u32 s15, s41, 0
	s_add_u32 s16, s40, 0x1e00900
	s_addc_u32 s17, s41, 0
	s_add_u32 s18, s40, 0x1e00a00
	s_addc_u32 s19, s41, 0
	s_add_u32 s20, s40, 0x1e00b00
	s_addc_u32 s21, s41, 0
	s_add_u32 s22, s40, 0x1e00c00
	s_addc_u32 s23, s41, 0
	s_add_u32 s24, s40, 0x1e00d00
	s_addc_u32 s25, s41, 0
	s_add_u32 s26, s40, 0x1e00e00
	s_addc_u32 s27, s41, 0
	s_add_u32 s28, s40, 0x1e00f00
	s_addc_u32 s29, s41, 0
	s_add_u32 s30, s40, 0x1e01000
	s_addc_u32 s31, s41, 0
	s_add_u32 s34, s40, 0x1e01100
	s_addc_u32 s35, s41, 0
	s_add_u32 s36, s40, 0x1e01200
	s_addc_u32 s37, s41, 0
	s_mul_i32 s33, s53, s56
	s_add_u32 s38, s40, 0x1e01300
	s_mul_i32 s33, s33, s52
	s_addc_u32 s39, s41, 0
	s_mov_b32 s50, 1
	v_mov_b32_e32 v18, 0
	s_branch .LBB0_839

.LBB0_1064:
	s_waitcnt vmcnt(0)
	s_waitcnt vmcnt(0)
	s_barrier
	v_readlane_b32 s98, v253, 56
	s_nop 0
	s_cmp_lg_u32 s98, 32
	s_cbranch_scc1 .Lb4_6
	s_mov_b64 s[98:99], exec
	s_mov_b64 exec, -1
	buffer_inv sc1
	s_waitcnt vmcnt(0)
	s_mov_b64 exec, s[98:99]
.Lb4_6:
	s_and_saveexec_b64 s[0:1], s[6:7]
	s_cbranch_execz .LBB0_1116
	v_readlane_b32 s6, v253, 60
	s_waitcnt vmcnt(0) expcnt(0) lgkmcnt(0)
	s_nop 0
	v_mov_b32_e32 v0, s6
	ds_read_b32 v2, v0
	v_readlane_b32 s6, v253, 61
	s_waitcnt lgkmcnt(0)
	v_cmp_ne_u32_e32 vcc, 0, v2
	v_mov_b32_e32 v0, s6
	ds_read_b32 v0, v0
	s_cbranch_vccnz .LBB0_1080
	s_mov_b32 s12, 1
	s_branch .LBB0_1068

.Lb4_7:
	s_and_saveexec_b64 s[0:1], s[4:5]
	s_cbranch_execz .LBB0_901
	v_readlane_b32 s4, v253, 60
	s_waitcnt vmcnt(0) expcnt(0) lgkmcnt(0)
	s_nop 0
	v_mov_b32_e32 v0, s4
	ds_read_b32 v2, v0
	v_readlane_b32 s4, v253, 61
	s_waitcnt lgkmcnt(0)
	v_cmp_ne_u32_e32 vcc, 0, v2
	v_mov_b32_e32 v0, s4
	ds_read_b32 v0, v0
	s_cbranch_vccnz .LBB0_1459
	s_mov_b32 s10, 1
	s_branch .LBB0_1447

.Lsm7_done:
	s_nop 0
	s_waitcnt vmcnt(0)
	s_branch .LBB0_901
